# diff-attn: fix stale vmcnt waits, pipelined tile block, prefetch distance 2; DSA: streamlined 16 insert sites
# speedup vs baseline: 1.0379x; 1.0379x over previous
.LBB0_370:
	ds_read_b128 v[2:5], v151
	ds_read_b128 v[160:163], v151 offset:32
	s_lshl_b32 s2, s29, 7
	v_cndmask_b32_e64 v158, v155, v157, s[6:7]
	s_cmp_le_u32 s2, s22
	s_waitcnt lgkmcnt(1)
	v_mfma_f32_32x32x16_bf16 v[50:65], v[66:69], v[2:5], 0
	ds_read_b128 v[2:5], v151 offset:4608
	s_cselect_b64 s[18:19], -1, 0
	s_waitcnt lgkmcnt(1)
	v_mfma_f32_32x32x16_bf16 v[50:65], v[70:73], v[160:163], v[50:65]
	ds_read_b128 v[160:163], v151 offset:4640
	s_waitcnt lgkmcnt(1)
	v_mfma_f32_32x32x16_bf16 v[34:49], v[66:69], v[2:5], 0
	ds_read_b128 v[2:5], v151 offset:9216
	s_waitcnt lgkmcnt(1)
	v_mfma_f32_32x32x16_bf16 v[34:49], v[70:73], v[160:163], v[34:49]
	ds_read_b128 v[160:163], v151 offset:9248
	s_waitcnt lgkmcnt(1)
	v_mfma_f32_32x32x16_bf16 v[18:33], v[66:69], v[2:5], 0
	ds_read_b128 v[2:5], v151 offset:13824
	s_waitcnt lgkmcnt(1)
	v_mfma_f32_32x32x16_bf16 v[18:33], v[70:73], v[160:163], v[18:33]
	ds_read_b128 v[160:163], v151 offset:13856
	s_waitcnt lgkmcnt(1)
	v_mfma_f32_32x32x16_bf16 v[2:17], v[66:69], v[2:5], 0
	s_waitcnt lgkmcnt(0)
	v_mfma_f32_32x32x16_bf16 v[2:17], v[70:73], v[160:163], v[2:17]
	ds_read_b128 v[160:163], v151 offset:64
	s_waitcnt lgkmcnt(0)
	v_mfma_f32_32x32x16_bf16 v[50:65], v[74:77], v[160:163], v[50:65]
	ds_read_b128 v[160:163], v151 offset:4672
	s_waitcnt lgkmcnt(0)
	v_mfma_f32_32x32x16_bf16 v[34:49], v[74:77], v[160:163], v[34:49]
	ds_read_b128 v[160:163], v151 offset:9280
	s_waitcnt lgkmcnt(0)
	v_mfma_f32_32x32x16_bf16 v[18:33], v[74:77], v[160:163], v[18:33]
	ds_read_b128 v[160:163], v151 offset:13888
	s_waitcnt lgkmcnt(0)
	v_mfma_f32_32x32x16_bf16 v[2:17], v[74:77], v[160:163], v[2:17]
	ds_read_b128 v[160:163], v151 offset:96
	s_waitcnt lgkmcnt(0)
	v_mfma_f32_32x32x16_bf16 v[50:65], v[78:81], v[160:163], v[50:65]
	ds_read_b128 v[160:163], v151 offset:4704
	s_waitcnt lgkmcnt(0)
	v_mfma_f32_32x32x16_bf16 v[34:49], v[78:81], v[160:163], v[34:49]
	s_nop 8
	v_fma_f32 v159, v107, v50, 0
	v_fma_f32 v50, v107, |v50|, v159
	v_fmac_f32_e32 v50, v108, v51
	v_fma_f32 v50, v108, |v51|, v50
	v_fmac_f32_e32 v50, v115, v52
	ds_read_b128 v[160:163], v151 offset:9312
	v_fma_f32 v50, v115, |v52|, v50
	v_fmac_f32_e32 v50, v116, v53
	v_fma_f32 v50, v116, |v53|, v50
	v_fmac_f32_e32 v50, v119, v54
	v_fma_f32 v50, v119, |v54|, v50
	s_waitcnt lgkmcnt(0)
	v_mfma_f32_32x32x16_bf16 v[18:33], v[78:81], v[160:163], v[18:33]
	ds_read_b128 v[160:163], v151 offset:13920
	v_fmac_f32_e32 v50, v120, v55
	v_fma_f32 v50, v120, |v55|, v50
	v_fmac_f32_e32 v50, v125, v56
	v_fma_f32 v50, v125, |v56|, v50
	v_fmac_f32_e32 v50, v126, v57
	v_fma_f32 v50, v126, |v57|, v50
	s_waitcnt lgkmcnt(0)
	v_mfma_f32_32x32x16_bf16 v[2:17], v[78:81], v[160:163], v[2:17]
	v_ashrrev_i32_e32 v52, 31, v50
	v_or_b32_e32 v51, s2, v128
	v_bitop3_b32 v50, v52, v50, s92 bitop3:0x36
	v_and_or_b32 v50, v50, s5, v51
	v_cmp_gt_u32_e32 vcc, v50, v158
	s_and_b64 vcc, vcc, s[18:19]
	s_cbranch_vccz .LBB0_376
	s_bcnt1_i32_b32 s3, vcc_lo
	v_mbcnt_lo_u32_b32 v53, vcc_lo, 0
	s_sub_i32 s12, s26, s3
	v_mbcnt_hi_u32_b32 v53, vcc_hi, v53
	s_addk_i32 s12, 0x600
	v_sub_u32_e32 v54, s12, v144
	s_bcnt1_i32_b32 s13, vcc_hi
	v_and_b32_e32 v54, v54, v148
	v_add3_u32 v53, v53, v144, v54
	v_lshl_add_u32 v53, v53, 2, v129
	s_mov_b64 exec, vcc
	ds_write_b32 v53, v50
	s_mov_b64 exec, -1
	v_add_u32_e32 v144, s3, v144
	s_add_i32 s26, s13, s26
.LBB0_376:
	v_fma_f32 v50, v109, v58, 0
	v_fma_f32 v50, v109, |v58|, v50
	v_fmac_f32_e32 v50, v114, v59
	v_fma_f32 v50, v114, |v59|, v50
	v_fmac_f32_e32 v50, v117, v60
	v_fma_f32 v50, v117, |v60|, v50
	v_fmac_f32_e32 v50, v118, v61
	v_fma_f32 v50, v118, |v61|, v50
	v_fmac_f32_e32 v50, v121, v62
	v_fma_f32 v50, v121, |v62|, v50
	v_fmac_f32_e32 v50, v124, v63
	v_fma_f32 v50, v124, |v63|, v50
	v_fmac_f32_e32 v50, v127, v64
	v_fma_f32 v50, v127, |v64|, v50
	v_fmac_f32_e32 v50, v146, v65
	v_fma_f32 v52, v146, |v65|, v50
	v_ashrrev_i32_e32 v53, 31, v52
	v_bitop3_b32 v52, v53, v52, s92 bitop3:0x36
	v_cndmask_b32_e64 v50, v154, v156, s[6:7]
	v_and_or_b32 v51, v52, s5, v51
	v_cmp_gt_u32_e32 vcc, v51, v50
	s_and_b64 vcc, vcc, s[18:19]
	s_cbranch_vccz .LBB0_382
	s_bcnt1_i32_b32 s3, vcc_lo
	v_mbcnt_lo_u32_b32 v53, vcc_lo, 0
	s_sub_i32 s12, s27, s3
	v_mbcnt_hi_u32_b32 v53, vcc_hi, v53
	s_addk_i32 s12, 0x600
	v_sub_u32_e32 v54, s12, v145
	s_bcnt1_i32_b32 s13, vcc_hi
	v_and_b32_e32 v54, v54, v148
	v_add3_u32 v53, v53, v145, v54
	v_lshl_add_u32 v53, v53, 2, v129
	s_mov_b64 exec, vcc
	ds_write_b32 v53, v51 offset:3072
	s_mov_b64 exec, -1
	v_add_u32_e32 v145, s3, v145
	s_add_i32 s27, s13, s27
.LBB0_382:
	v_fma_f32 v51, v107, v34, 0
	v_fma_f32 v34, v107, |v34|, v51
	v_fmac_f32_e32 v34, v108, v35
	v_fma_f32 v34, v108, |v35|, v34
	v_fmac_f32_e32 v34, v115, v36
	v_fma_f32 v34, v115, |v36|, v34
	v_fmac_f32_e32 v34, v116, v37
	v_fma_f32 v34, v116, |v37|, v34
	v_fmac_f32_e32 v34, v119, v38
	v_fma_f32 v34, v119, |v38|, v34
	v_fmac_f32_e32 v34, v120, v39
	v_fma_f32 v34, v120, |v39|, v34
	v_fmac_f32_e32 v34, v125, v40
	v_fma_f32 v34, v125, |v40|, v34
	v_fmac_f32_e32 v34, v126, v41
	v_fma_f32 v35, v126, |v41|, v34
	s_or_b32 s3, s2, 32
	v_ashrrev_i32_e32 v36, 31, v35
	v_or_b32_e32 v34, s3, v128
	v_bitop3_b32 v35, v36, v35, s92 bitop3:0x36
	s_cmp_lt_u32 s3, s23
	v_and_or_b32 v35, v35, s5, v34
	s_cselect_b64 s[18:19], -1, 0
	v_cmp_gt_u32_e32 vcc, v35, v158
	s_and_b64 vcc, vcc, s[18:19]
	s_cbranch_vccz .LBB0_388
	s_bcnt1_i32_b32 s3, vcc_lo
	v_mbcnt_lo_u32_b32 v37, vcc_lo, 0
	s_sub_i32 s12, s26, s3
	v_mbcnt_hi_u32_b32 v37, vcc_hi, v37
	s_addk_i32 s12, 0x600
	v_sub_u32_e32 v38, s12, v144
	s_bcnt1_i32_b32 s13, vcc_hi
	v_and_b32_e32 v38, v38, v148
	v_add3_u32 v37, v37, v144, v38
	v_lshl_add_u32 v37, v37, 2, v129
	s_mov_b64 exec, vcc
	ds_write_b32 v37, v35
	s_mov_b64 exec, -1
	v_add_u32_e32 v144, s3, v144
	s_add_i32 s26, s13, s26
.LBB0_388:
	v_fma_f32 v35, v109, v42, 0
	v_fma_f32 v35, v109, |v42|, v35
	v_fmac_f32_e32 v35, v114, v43
	v_fma_f32 v35, v114, |v43|, v35
	v_fmac_f32_e32 v35, v117, v44
	v_fma_f32 v35, v117, |v44|, v35
	v_fmac_f32_e32 v35, v118, v45
	v_fma_f32 v35, v118, |v45|, v35
	v_fmac_f32_e32 v35, v121, v46
	v_fma_f32 v35, v121, |v46|, v35
	v_fmac_f32_e32 v35, v124, v47
	v_fma_f32 v35, v124, |v47|, v35
	v_fmac_f32_e32 v35, v127, v48
	v_fma_f32 v35, v127, |v48|, v35
	v_fmac_f32_e32 v35, v146, v49
	v_fma_f32 v35, v146, |v49|, v35
	v_ashrrev_i32_e32 v36, 31, v35
	v_bitop3_b32 v35, v36, v35, s92 bitop3:0x36
	v_and_or_b32 v34, v35, s5, v34
	v_cmp_gt_u32_e32 vcc, v34, v50
	s_and_b64 vcc, vcc, s[18:19]
	s_cbranch_vccz .LBB0_394
	s_bcnt1_i32_b32 s3, vcc_lo
	v_mbcnt_lo_u32_b32 v36, vcc_lo, 0
	s_sub_i32 s12, s27, s3
	v_mbcnt_hi_u32_b32 v36, vcc_hi, v36
	s_addk_i32 s12, 0x600
	v_sub_u32_e32 v37, s12, v145
	s_bcnt1_i32_b32 s13, vcc_hi
	v_and_b32_e32 v37, v37, v148
	v_add3_u32 v36, v36, v145, v37
	v_lshl_add_u32 v36, v36, 2, v129
	s_mov_b64 exec, vcc
	ds_write_b32 v36, v34 offset:3072
	s_mov_b64 exec, -1
	v_add_u32_e32 v145, s3, v145
	s_add_i32 s27, s13, s27
.LBB0_394:
	v_fma_f32 v34, v107, v18, 0
	v_fma_f32 v18, v107, |v18|, v34
	v_fmac_f32_e32 v18, v108, v19
	v_fma_f32 v18, v108, |v19|, v18
	v_fmac_f32_e32 v18, v115, v20
	v_fma_f32 v18, v115, |v20|, v18
	v_fmac_f32_e32 v18, v116, v21
	v_fma_f32 v18, v116, |v21|, v18
	v_fmac_f32_e32 v18, v119, v22
	v_fma_f32 v18, v119, |v22|, v18
	v_fmac_f32_e32 v18, v120, v23
	v_fma_f32 v18, v120, |v23|, v18
	v_fmac_f32_e32 v18, v125, v24
	v_fma_f32 v18, v125, |v24|, v18
	v_fmac_f32_e32 v18, v126, v25
	v_fma_f32 v19, v126, |v25|, v18
	v_ashrrev_i32_e32 v20, 31, v19
	v_or_b32_e32 v18, s2, v150
	v_bitop3_b32 v19, v20, v19, s92 bitop3:0x36
	s_cmp_lt_u32 s2, s22
	v_and_or_b32 v19, v19, s5, v18
	s_cselect_b64 s[18:19], -1, 0
	v_cmp_gt_u32_e32 vcc, v19, v158
	s_and_b64 vcc, vcc, s[18:19]
	s_cbranch_vccz .LBB0_400
	s_bcnt1_i32_b32 s3, vcc_lo
	v_mbcnt_lo_u32_b32 v21, vcc_lo, 0
	s_sub_i32 s12, s26, s3
	v_mbcnt_hi_u32_b32 v21, vcc_hi, v21
	s_addk_i32 s12, 0x600
	v_sub_u32_e32 v22, s12, v144
	s_bcnt1_i32_b32 s13, vcc_hi
	v_and_b32_e32 v22, v22, v148
	v_add3_u32 v21, v21, v144, v22
	v_lshl_add_u32 v21, v21, 2, v129
	s_mov_b64 exec, vcc
	ds_write_b32 v21, v19
	s_mov_b64 exec, -1
	v_add_u32_e32 v144, s3, v144
	s_add_i32 s26, s13, s26
.LBB0_400:
	v_fma_f32 v19, v109, v26, 0
	v_fma_f32 v19, v109, |v26|, v19
	v_fmac_f32_e32 v19, v114, v27
	v_fma_f32 v19, v114, |v27|, v19
	v_fmac_f32_e32 v19, v117, v28
	v_fma_f32 v19, v117, |v28|, v19
	v_fmac_f32_e32 v19, v118, v29
	v_fma_f32 v19, v118, |v29|, v19
	v_fmac_f32_e32 v19, v121, v30
	v_fma_f32 v19, v121, |v30|, v19
	v_fmac_f32_e32 v19, v124, v31
	v_fma_f32 v19, v124, |v31|, v19
	v_fmac_f32_e32 v19, v127, v32
	v_fma_f32 v19, v127, |v32|, v19
	v_fmac_f32_e32 v19, v146, v33
	v_fma_f32 v19, v146, |v33|, v19
	v_ashrrev_i32_e32 v20, 31, v19
	v_bitop3_b32 v19, v20, v19, s92 bitop3:0x36
	v_and_or_b32 v18, v19, s5, v18
	v_cmp_gt_u32_e32 vcc, v18, v50
	s_and_b64 vcc, vcc, s[18:19]
	s_cbranch_vccz .LBB0_406
	s_bcnt1_i32_b32 s3, vcc_lo
	v_mbcnt_lo_u32_b32 v20, vcc_lo, 0
	s_sub_i32 s12, s27, s3
	v_mbcnt_hi_u32_b32 v20, vcc_hi, v20
	s_addk_i32 s12, 0x600
	v_sub_u32_e32 v21, s12, v145
	s_bcnt1_i32_b32 s13, vcc_hi
	v_and_b32_e32 v21, v21, v148
	v_add3_u32 v20, v20, v145, v21
	v_lshl_add_u32 v20, v20, 2, v129
	s_mov_b64 exec, vcc
	ds_write_b32 v20, v18 offset:3072
	s_mov_b64 exec, -1
	v_add_u32_e32 v145, s3, v145
	s_add_i32 s27, s13, s27
.LBB0_406:
	v_fma_f32 v18, v107, v2, 0
	v_fma_f32 v2, v107, |v2|, v18
	v_fmac_f32_e32 v2, v108, v3
	v_fma_f32 v2, v108, |v3|, v2
	v_fmac_f32_e32 v2, v115, v4
	v_fma_f32 v2, v115, |v4|, v2
	v_fmac_f32_e32 v2, v116, v5
	v_fma_f32 v2, v116, |v5|, v2
	v_fmac_f32_e32 v2, v119, v6
	v_fma_f32 v2, v119, |v6|, v2
	v_fmac_f32_e32 v2, v120, v7
	v_fma_f32 v2, v120, |v7|, v2
	v_fmac_f32_e32 v2, v125, v8
	v_fma_f32 v2, v125, |v8|, v2
	v_fmac_f32_e32 v2, v126, v9
	v_fma_f32 v3, v126, |v9|, v2
	s_or_b32 s2, s2, 0x60
	v_ashrrev_i32_e32 v4, 31, v3
	v_or_b32_e32 v2, s2, v128
	v_bitop3_b32 v3, v4, v3, s92 bitop3:0x36
	s_cmp_lt_u32 s2, s23
	v_and_or_b32 v3, v3, s5, v2
	s_cselect_b64 s[18:19], -1, 0
	v_cmp_gt_u32_e32 vcc, v3, v158
	s_and_b64 vcc, vcc, s[18:19]
	s_cbranch_vccz .LBB0_412
	s_bcnt1_i32_b32 s3, vcc_lo
	v_mbcnt_lo_u32_b32 v5, vcc_lo, 0
	s_sub_i32 s12, s26, s3
	v_mbcnt_hi_u32_b32 v5, vcc_hi, v5
	s_addk_i32 s12, 0x600
	v_sub_u32_e32 v6, s12, v144
	s_bcnt1_i32_b32 s13, vcc_hi
	v_and_b32_e32 v6, v6, v148
	v_add3_u32 v5, v5, v144, v6
	v_lshl_add_u32 v5, v5, 2, v129
	s_mov_b64 exec, vcc
	ds_write_b32 v5, v3
	s_mov_b64 exec, -1
	v_add_u32_e32 v144, s3, v144
	s_add_i32 s26, s13, s26
.LBB0_412:
	v_fma_f32 v3, v109, v10, 0
	v_fma_f32 v3, v109, |v10|, v3
	v_fmac_f32_e32 v3, v114, v11
	v_fma_f32 v3, v114, |v11|, v3
	v_fmac_f32_e32 v3, v117, v12
	v_fma_f32 v3, v117, |v12|, v3
	v_fmac_f32_e32 v3, v118, v13
	v_fma_f32 v3, v118, |v13|, v3
	v_fmac_f32_e32 v3, v121, v14
	v_fma_f32 v3, v121, |v14|, v3
	v_fmac_f32_e32 v3, v124, v15
	v_fma_f32 v3, v124, |v15|, v3
	v_fmac_f32_e32 v3, v127, v16
	v_fma_f32 v3, v127, |v16|, v3
	v_fmac_f32_e32 v3, v146, v17
	v_fma_f32 v3, v146, |v17|, v3
	v_ashrrev_i32_e32 v4, 31, v3
	v_bitop3_b32 v3, v4, v3, s92 bitop3:0x36
	v_and_or_b32 v2, v3, s5, v2
	v_cmp_gt_u32_e32 vcc, v2, v50
	s_and_b64 vcc, vcc, s[18:19]
	s_cbranch_vccz .LBB0_418
	s_bcnt1_i32_b32 s3, vcc_lo
	v_mbcnt_lo_u32_b32 v4, vcc_lo, 0
	s_sub_i32 s12, s27, s3
	v_mbcnt_hi_u32_b32 v4, vcc_hi, v4
	s_addk_i32 s12, 0x600
	v_sub_u32_e32 v5, s12, v145
	s_bcnt1_i32_b32 s13, vcc_hi
	v_and_b32_e32 v5, v5, v148
	v_add3_u32 v4, v4, v145, v5
	v_lshl_add_u32 v4, v4, 2, v129
	s_mov_b64 exec, vcc
	ds_write_b32 v4, v2 offset:3072
	s_mov_b64 exec, -1
	v_add_u32_e32 v145, s3, v145
	s_add_i32 s27, s13, s27

.LBB0_551:
	ds_read_b128 v[2:5], v153
	ds_read_b128 v[160:163], v153 offset:32
	s_lshl_b32 s2, s2, 7
	v_cndmask_b32_e64 v158, v155, v157, s[6:7]
	s_cmp_le_u32 s2, s22
	s_waitcnt lgkmcnt(1)
	v_mfma_f32_32x32x16_bf16 v[50:65], v[66:69], v[2:5], 0
	ds_read_b128 v[2:5], v153 offset:4608
	s_cselect_b64 s[18:19], -1, 0
	s_waitcnt lgkmcnt(1)
	v_mfma_f32_32x32x16_bf16 v[50:65], v[70:73], v[160:163], v[50:65]
	ds_read_b128 v[160:163], v153 offset:4640
	s_waitcnt lgkmcnt(1)
	v_mfma_f32_32x32x16_bf16 v[34:49], v[66:69], v[2:5], 0
	ds_read_b128 v[2:5], v153 offset:9216
	s_waitcnt lgkmcnt(1)
	v_mfma_f32_32x32x16_bf16 v[34:49], v[70:73], v[160:163], v[34:49]
	ds_read_b128 v[160:163], v153 offset:9248
	s_waitcnt lgkmcnt(1)
	v_mfma_f32_32x32x16_bf16 v[18:33], v[66:69], v[2:5], 0
	ds_read_b128 v[2:5], v153 offset:13824
	s_waitcnt lgkmcnt(1)
	v_mfma_f32_32x32x16_bf16 v[18:33], v[70:73], v[160:163], v[18:33]
	ds_read_b128 v[160:163], v153 offset:13856
	s_waitcnt lgkmcnt(1)
	v_mfma_f32_32x32x16_bf16 v[2:17], v[66:69], v[2:5], 0
	s_waitcnt lgkmcnt(0)
	v_mfma_f32_32x32x16_bf16 v[2:17], v[70:73], v[160:163], v[2:17]
	ds_read_b128 v[160:163], v153 offset:64
	s_waitcnt lgkmcnt(0)
	v_mfma_f32_32x32x16_bf16 v[50:65], v[74:77], v[160:163], v[50:65]
	ds_read_b128 v[160:163], v153 offset:4672
	s_waitcnt lgkmcnt(0)
	v_mfma_f32_32x32x16_bf16 v[34:49], v[74:77], v[160:163], v[34:49]
	ds_read_b128 v[160:163], v153 offset:9280
	s_waitcnt lgkmcnt(0)
	v_mfma_f32_32x32x16_bf16 v[18:33], v[74:77], v[160:163], v[18:33]
	ds_read_b128 v[160:163], v153 offset:13888
	s_waitcnt lgkmcnt(0)
	v_mfma_f32_32x32x16_bf16 v[2:17], v[74:77], v[160:163], v[2:17]
	ds_read_b128 v[160:163], v153 offset:96
	s_waitcnt lgkmcnt(0)
	v_mfma_f32_32x32x16_bf16 v[50:65], v[78:81], v[160:163], v[50:65]
	ds_read_b128 v[160:163], v153 offset:4704
	s_waitcnt lgkmcnt(0)
	v_mfma_f32_32x32x16_bf16 v[34:49], v[78:81], v[160:163], v[34:49]
	s_nop 8
	v_fma_f32 v159, v107, v50, 0
	v_fma_f32 v50, v107, |v50|, v159
	v_fmac_f32_e32 v50, v108, v51
	v_fma_f32 v50, v108, |v51|, v50
	v_fmac_f32_e32 v50, v115, v52
	ds_read_b128 v[160:163], v153 offset:9312
	v_fma_f32 v50, v115, |v52|, v50
	v_fmac_f32_e32 v50, v116, v53
	v_fma_f32 v50, v116, |v53|, v50
	v_fmac_f32_e32 v50, v119, v54
	v_fma_f32 v50, v119, |v54|, v50
	s_waitcnt lgkmcnt(0)
	v_mfma_f32_32x32x16_bf16 v[18:33], v[78:81], v[160:163], v[18:33]
	ds_read_b128 v[160:163], v153 offset:13920
	v_fmac_f32_e32 v50, v120, v55
	v_fma_f32 v50, v120, |v55|, v50
	v_fmac_f32_e32 v50, v125, v56
	v_fma_f32 v50, v125, |v56|, v50
	v_fmac_f32_e32 v50, v126, v57
	v_fma_f32 v50, v126, |v57|, v50
	s_waitcnt lgkmcnt(0)
	v_mfma_f32_32x32x16_bf16 v[2:17], v[78:81], v[160:163], v[2:17]
	v_ashrrev_i32_e32 v52, 31, v50
	v_or_b32_e32 v51, s2, v128
	v_bitop3_b32 v50, v52, v50, s92 bitop3:0x36
	v_and_or_b32 v50, v50, s5, v51
	v_cmp_gt_u32_e32 vcc, v50, v158
	s_and_b64 vcc, vcc, s[18:19]
	s_cbranch_vccz .LBB0_557
	s_bcnt1_i32_b32 s3, vcc_lo
	v_mbcnt_lo_u32_b32 v53, vcc_lo, 0
	s_sub_i32 s12, s26, s3
	v_mbcnt_hi_u32_b32 v53, vcc_hi, v53
	s_addk_i32 s12, 0x600
	v_sub_u32_e32 v54, s12, v144
	s_bcnt1_i32_b32 s13, vcc_hi
	v_and_b32_e32 v54, v54, v148
	v_add3_u32 v53, v53, v144, v54
	v_lshl_add_u32 v53, v53, 2, v129
	s_mov_b64 exec, vcc
	ds_write_b32 v53, v50
	s_mov_b64 exec, -1
	v_add_u32_e32 v144, s3, v144
	s_add_i32 s26, s13, s26

; #define LAS __attribute__((address_space(3)))
; DI f32x16 zero16() { f32x16 z; for (int i = 0; i < 16; ++i) z[i] = 0.f; return z; }
; template <int MODE>
; DI void dense256_unit(const Params& p, int l, int b, int nq, int hd, LAS unsigned char* lds) {
;     ...
;   int tid_ = threadIdx.x; asm volatile("" : "+v"(tid_)); const int tid = tid_, lane = tid & 63, w = tid >> 6, r = lane & 31, h = lane >> 5, qh = w & 1;
;   const int cw = 4 * nq + (w >> 1);
;   const u16* proj = (const u16*)(p.ws + WS_PROJ); u16* ybuf = (u16*)(p.ws + WS_XB);
;   const size_t tq = (size_t)b * S + cw * 64 + qh * 32 + r;
;   const int iq = qh * 32 + r;
;   bf16x8 qf[4];
; #pragma unroll
;   for (int s = 0; s < 4; ++s) qf[s] = *(const bf16x8*)(proj + tq * NP + QCOL + hd * 64 + 16 * s + 8 * h);
;   const int ntiles = 4 * nq + 4;
;   const int lrow = tid >> 3, lc16 = tid & 7;
;   const u16* kbase = proj + (size_t)b * S * NP + KCOL + hd * 64 + lc16 * 8; const u16* vbase = proj + (size_t)b * S * NP + VCOL + hd * 64 + lc16 * 8;
;   u32x4 kr, vr;
;   kr = *(const u32x4*)(kbase + (size_t)lrow * NP); vr = *(const u32x4*)(vbase + (size_t)lrow * NP);
;   *(LAS u32x4*)(lds + W_KOFF + lrow * W_RS + lc16 * 16) = kr; *(LAS u32x4*)(lds + W_VOFF + lrow * W_RS + lc16 * 16) = vr;
;   __syncthreads();
;   f32x16 o1[2] = {zero16(), zero16()}, o2[2] = {zero16(), zero16()};
;   float l1 = 0.f, l2 = 0.f;
;   const float lg2g = log2f(1.0f - exp2f(-5.0f - (float)hd));
;   const float cd = exp2f(lg2g * 64.0f);
;   (void)l2; (void)cd; (void)lg2g; (void)iq;
; #pragma unroll 1
;   for (int m = 0; m < ntiles; ++m) {
;     const int buf = m & 1; const bool has_next = m + 1 < ntiles;
;     if (has_next) { kr = *(const u32x4*)(kbase + (size_t)((m + 1) * 64 + lrow) * NP); vr = *(const u32x4*)(vbase + (size_t)((m + 1) * 64 + lrow) * NP); }
.LBB0_965:
	s_add_i32 s6, s78, -4
	v_mov_b32_e32 v15, v168
	s_lshl_b32 s7, s6, 2
	s_andn2_b32 s11, 0x7c, s7
	v_ashrrev_i32_e32 v0, 7, v15
	v_add_u32_e32 v123, s11, v0
	v_lshlrev_b32_e32 v2, 6, v123
	v_ashrrev_i32_e32 v3, 31, v2
	v_lshrrev_b32_e32 v0, 1, v15
	v_and_b32_e32 v18, 31, v15
	v_lshl_add_u64 v[124:125], v[2:3], 0, s[0:1]
	v_and_b32_e32 v0, 32, v0
	v_or3_b32 v124, v124, v0, v18
	v_mov_b64_e32 v[2:3], s[56:57]
	v_mad_u64_u32 v[126:127], s[2:3], v124, s85, v[2:3]
	s_lshl_b32 s2, s6, 1
	s_and_b32 s10, s2, 0x7fffffc0
	s_lshl_b32 s90, s10, 1
	s_add_i32 s11, s11, 4
	s_add_u32 s2, s93, s90
	v_readlane_b32 s3, v250, 4
	v_lshlrev_b32_e32 v0, 4, v15
	s_addc_u32 s3, s3, 0
	v_and_b32_e32 v16, 0x70, v0
	v_mov_b32_e32 v17, v1
	v_lshl_add_u64 v[4:5], s[2:3], 0, v[16:17]
	v_readlane_b32 s2, v250, 5
	s_add_u32 s2, s2, s90
	v_readlane_b32 s3, v250, 6
	s_addc_u32 s3, s3, 0
	v_bfe_u32 v19, v15, 5, 1
	v_mad_i32_i24 v127, v125, s85, v127
	v_ashrrev_i32_e32 v20, 3, v15
	v_lshl_add_u64 v[6:7], s[2:3], 0, v[16:17]
	v_lshl_add_u64 v[2:3], v[126:127], 0, s[90:91]
	v_mad_i64_i32 v[4:5], s[2:3], v20, s85, v[4:5]
	v_mad_i64_i32 v[6:7], s[2:3], v20, s85, v[6:7]
	v_lshlrev_b32_e32 v0, 4, v19
	v_lshl_add_u64 v[2:3], v[2:3], 0, v[0:1]
	s_mov_b64 s[2:3], 0x1180
	global_load_dwordx4 v[98:101], v[4:5], off
	global_load_dwordx4 v[102:105], v[6:7], off
	v_lshl_add_u64 v[4:5], v[2:3], 0, s[2:3]
	v_add_co_u32_e32 v2, vcc, s94, v2
	v_and_b32_e32 v190, 63, v15
	s_nop 0
	v_addc_co_u32_e32 v3, vcc, 0, v3, vcc
	global_load_dwordx4 v[106:109], v[4:5], off offset:32
	global_load_dwordx4 v[110:113], v[4:5], off offset:64
	global_load_dwordx4 v[114:117], v[2:3], off offset:384
	global_load_dwordx4 v[118:121], v[4:5], off offset:96
	v_lshrrev_b32_e32 v17, 2, v15
	v_and_b32_e32 v21, 16, v15
	v_lshlrev_b32_e32 v15, 2, v15
	v_lshlrev_b32_e32 v189, 2, v19
	v_and_or_b32 v15, v15, 12, v21
	v_mul_u32_u24_e32 v18, 0x90, v18
	v_and_or_b32 v17, v17, 3, v189
	v_lshlrev_b32_e32 v15, 1, v15
	v_add3_u32 v192, 0, v0, v18
	v_mul_u32_u24_e32 v0, 0x90, v17
	s_and_b32 s3, s7, 0xffffff80
	v_add3_u32 v193, 0, v0, v15
	v_mov_b32_e32 v0, s3
	v_mad_i64_i32 v[18:19], s[6:7], v20, s85, v[0:1]
	v_mul_lo_u32 v22, v20, s59
	v_readlane_b32 s6, v250, 9
	v_add3_u32 v191, 0, v22, v16
	v_or_b32_e32 v18, v18, v16
	v_readlane_b32 s7, v250, 10
	v_mov_b32_e32 v16, v1
	v_mov_b32_e32 v17, v1
	v_mov_b32_e32 v2, v1
	v_mov_b32_e32 v3, v1
	v_mov_b32_e32 v4, v1
	v_mov_b32_e32 v5, v1
	v_mov_b32_e32 v6, v1
	v_mov_b32_e32 v7, v1
	v_mov_b32_e32 v8, v1
	v_mov_b32_e32 v9, v1
	v_mov_b32_e32 v10, v1
	v_mov_b32_e32 v11, v1
	v_mov_b32_e32 v12, v1
	v_mov_b32_e32 v13, v1
	v_mov_b32_e32 v14, v1
	v_mov_b32_e32 v0, v1
	v_lshl_add_u64 v[128:129], s[6:7], 0, v[18:19]
	v_mov_b32_e32 v15, v1
	s_waitcnt vmcnt(10)
	v_mov_b64_e32 v[48:49], v[16:17]
	v_mov_b64_e32 v[32:33], v[16:17]
	s_waitcnt vmcnt(6)
	v_mov_b64_e32 v[64:65], v[16:17]
	s_mov_b32 s2, 0
	v_mov_b64_e32 v[46:47], v[14:15]
	v_mov_b64_e32 v[44:45], v[12:13]
	v_mov_b64_e32 v[42:43], v[10:11]
	v_mov_b64_e32 v[40:41], v[8:9]
	v_mov_b64_e32 v[38:39], v[6:7]
	v_mov_b64_e32 v[36:37], v[4:5]
	v_mov_b64_e32 v[34:35], v[2:3]
	v_mov_b64_e32 v[30:31], v[14:15]
	v_mov_b64_e32 v[28:29], v[12:13]
	v_mov_b64_e32 v[26:27], v[10:11]
	v_mov_b64_e32 v[24:25], v[8:9]
	v_mov_b64_e32 v[22:23], v[6:7]
	v_mov_b64_e32 v[20:21], v[4:5]
	v_mov_b64_e32 v[18:19], v[2:3]
	v_mov_b64_e32 v[62:63], v[14:15]
	v_mov_b64_e32 v[60:61], v[12:13]
	v_mov_b64_e32 v[58:59], v[10:11]
	v_mov_b64_e32 v[56:57], v[8:9]
	v_mov_b64_e32 v[54:55], v[6:7]
	v_mov_b64_e32 v[52:53], v[4:5]
	v_mov_b64_e32 v[50:51], v[2:3]
	v_mov_b64_e32 v[150:151], v[0:1]
	s_waitcnt vmcnt(5)
	ds_write_b128 v191, v[98:101]
	s_waitcnt vmcnt(4)
	ds_write_b128 v191, v[102:105] offset:18432
	v_lshlrev_b32_e32 v66, 4, v168
	ds_write_b128 v66, v[124:127] offset:40960
	s_waitcnt vmcnt(0) lgkmcnt(0)
	s_mov_b64 s[14:15], 0x88000
	global_load_dwordx4 v[130:133], v[128:129], off
	global_load_dwordx4 v[134:137], v[128:129], off offset:512
	v_lshl_add_u64 v[128:129], v[128:129], 0, s[14:15]
	s_barrier
.LBB0_966:
	s_add_i32 s12, s2, 1
	s_and_b32 s13, s2, 1
	s_add_i32 s3, s2, 2
	s_cmp_lt_u32 s3, s11
	s_cbranch_scc0 .Lmy_diff_noload
	s_cmp_eq_u32 s13, 0
	s_cbranch_scc0 .Lmy_diff_loadB
	global_load_dwordx4 v[98:101], v[128:129], off
	global_load_dwordx4 v[102:105], v[128:129], off offset:512
	s_branch .Lmy_diff_loaded
.Lmy_diff_loadB:
	global_load_dwordx4 v[130:133], v[128:129], off
	global_load_dwordx4 v[134:137], v[128:129], off offset:512
.Lmy_diff_loaded:
	v_lshl_add_u64 v[128:129], v[128:129], 0, s[14:15]
.Lmy_diff_noload:
	s_cmp_lt_u32 s12, s11
	s_cselect_b64 s[6:7], -1, 0
	v_cmp_le_i32_e32 vcc, s2, v123
	s_and_saveexec_b64 s[8:9], vcc
	s_cbranch_execnz .LBB0_973

; #define LAS __attribute__((address_space(3)))
; template <int MODE>
; DI void dense256_unit(const Params& p, int l, int b, int nq, int hd, LAS unsigned char* lds) {
;     ...
;   for (int m = 0; m < ntiles; ++m) {
;     const int buf = m & 1; const bool has_next = m + 1 < ntiles;
;     if (has_next) { kr = *(const u32x4*)(kbase + (size_t)((m + 1) * 64 + lrow) * NP); vr = *(const u32x4*)(vbase + (size_t)((m + 1) * 64 + lrow) * NP); }
;     if (m <= cw) {
;       LAS unsigned char* kt = lds + W_KOFF + buf * W_TILE; LAS unsigned char* vt = lds + W_VOFF + buf * W_TILE;
;       const bool diag = (m == cw);
;       if (MODE == 1) { if (m >= 1 && !diag) { o1[0] *= cd; o1[1] *= cd; } }
; #pragma unroll
;       for (int mt = 0; mt < 2; ++mt) {
;         LAS unsigned char* krow = kt + (32 * mt + r) * W_RS + (8 * h) * 2;
;         const bf16x8 a0 = *(const LAS bf16x8*)(krow), a1 = *(const LAS bf16x8*)(krow + 32), a2 = *(const LAS bf16x8*)(krow + 64), a3 = *(const LAS bf16x8*)(krow + 96);
;         if (MODE == 0) {
;           f32x16 s1 = zero16(), s2 = zero16();
;           s1 = MFMA32(a0, qf[0], s1); s1 = MFMA32(a1, qf[1], s1); s2 = MFMA32(a2, qf[2], s2); s2 = MFMA32(a3, qf[3], s2);
; #pragma unroll
;           for (int i = 0; i < 16; ++i) { s1[i] = fexp2(s1[i]); l1 += s1[i]; s2[i] = fexp2(s2[i]); l2 += s2[i]; }
; #pragma unroll
;           for (int s = 0; s < 2; ++s) {
;             const bf16x8 p1 = pack8(s1, s), p2 = pack8(s2, s);
; #pragma unroll
;             for (int et = 0; et < 2; ++et) { const bf16x8 vf = vfrag144(vt, 32 * mt + 16 * s + 4 * h, 32 * et, lane); o1[et] = MFMA32(vf, p1, o1[et]); o2[et] = MFMA32(vf, p2, o2[et]); }
;           }
;         } else {
;           f32x16 sc = zero16();
;           sc = MFMA32(a0, qf[0], sc); sc = MFMA32(a1, qf[1], sc); sc = MFMA32(a2, qf[2], sc); sc = MFMA32(a3, qf[3], sc);
;           if (diag) {
; #pragma unroll
;             for (int i = 0; i < 16; ++i) { const int jk = 32 * mt + crow(i, h); const float e = (jk <= iq) ? -64.0f : (float)(2 * (jk - iq) - 64); sc[i] *= fexp2(lg2g * e); }
;           }
; #pragma unroll
;           for (int s = 0; s < 2; ++s) {
;             const bf16x8 p1 = pack8(sc, s);
; #pragma unroll
;             for (int et = 0; et < 2; ++et) { const bf16x8 vf = vfrag144(vt, 32 * mt + 16 * s + 4 * h, 32 * et, lane); o1[et] = MFMA32(vf, p1, o1[et]); }
;           }
;         }
;       }
;     }
.LBB0_969:
	s_xor_b32 s2, s13, 1
	s_mulk_i32 s2, 0x2400
	v_add_u32_e32 v0, s2, v191
	s_add_i32 s3, s12, 1
	s_cmp_lt_u32 s3, s11
	s_cbranch_scc1 .Lmy_diff_wait2
	s_waitcnt vmcnt(0)
	s_branch .Lmy_diff_waited
.Lmy_diff_wait2:
	s_waitcnt vmcnt(2)
.Lmy_diff_waited:
	s_cmp_eq_u32 s13, 0
	s_cbranch_scc0 .Lmy_diff_storeA
	ds_write_b128 v0, v[130:133]
	ds_write_b128 v0, v[134:137] offset:18432
	s_branch .LBB0_970
.Lmy_diff_storeA:
	ds_write_b128 v0, v[98:101]
	ds_write_b128 v0, v[102:105] offset:18432
.LBB0_970:
	s_cmp_eq_u32 s11, s12
	s_waitcnt lgkmcnt(0)
	s_barrier
	s_cbranch_scc1 .LBB0_974
	s_mov_b32 s2, s12
	s_branch .LBB0_966
.LBB0_973:
	s_cmp_eq_u32 s13, 0
	s_cbranch_scc0 .Lmy_diff_buf1
	ds_read_b128 v[156:159], v192
	ds_read_b128 v[160:163], v192 offset:32
	s_waitcnt lgkmcnt(1)
	v_mfma_f32_32x32x16_bf16 v[66:81], v[156:159], v[114:117], 0
	ds_read_b128 v[156:159], v192 offset:64
	s_waitcnt lgkmcnt(1)
	v_mfma_f32_32x32x16_bf16 v[66:81], v[160:163], v[106:109], v[66:81]
	ds_read_b128 v[160:163], v192 offset:96
	s_nop 10
	s_waitcnt lgkmcnt(1)
	v_mfma_f32_32x32x16_bf16 v[82:97], v[156:159], v[110:113], 0
	ds_read_b128 v[156:159], v192 offset:4608
	v_exp_f32_e32 v66, v66
	v_exp_f32_e32 v67, v67
	v_exp_f32_e32 v68, v68
	v_exp_f32_e32 v69, v69
	v_exp_f32_e32 v70, v70
	v_exp_f32_e32 v71, v71
	v_exp_f32_e32 v72, v72
	v_exp_f32_e32 v73, v73
	v_add_f32_e32 v151, v151, v66
	v_add_f32_e32 v151, v151, v67
	v_add_f32_e32 v151, v151, v68
	v_add_f32_e32 v151, v151, v69
	v_exp_f32_e32 v74, v74
	v_exp_f32_e32 v75, v75
	v_exp_f32_e32 v76, v76
	v_exp_f32_e32 v77, v77
	v_exp_f32_e32 v78, v78
	v_exp_f32_e32 v79, v79
	v_exp_f32_e32 v80, v80
	v_exp_f32_e32 v81, v81
	s_waitcnt lgkmcnt(1)
	v_mfma_f32_32x32x16_bf16 v[82:97], v[160:163], v[118:121], v[82:97]
	ds_read_b128 v[160:163], v192 offset:4640
	v_add_f32_e32 v151, v151, v70
	v_add_f32_e32 v151, v151, v71
	v_add_f32_e32 v151, v151, v72
	v_add_f32_e32 v151, v151, v73
	v_add_f32_e32 v151, v151, v74
	v_add_f32_e32 v151, v151, v75
	v_add_f32_e32 v151, v151, v76
	v_add_f32_e32 v151, v151, v77
	v_add_f32_e32 v151, v151, v78
	v_add_f32_e32 v151, v151, v79
	v_add_f32_e32 v151, v151, v80
	v_add_f32_e32 v151, v151, v81
	v_cvt_pk_bf16_f32 v138, v66, v67
	v_cvt_pk_bf16_f32 v139, v68, v69
	v_cvt_pk_bf16_f32 v140, v70, v71
	v_cvt_pk_bf16_f32 v141, v72, v73
	v_cvt_pk_bf16_f32 v142, v74, v75
	v_cvt_pk_bf16_f32 v143, v76, v77
	v_cvt_pk_bf16_f32 v144, v78, v79
	v_cvt_pk_bf16_f32 v145, v80, v81
	ds_read_b64_tr_b16 v[164:165], v193 offset:18432
	ds_read_b64_tr_b16 v[166:167], v193 offset:19584
	ds_read_b64_tr_b16 v[124:125], v193 offset:18496
	ds_read_b64_tr_b16 v[126:127], v193 offset:19648
	s_waitcnt lgkmcnt(5)
	v_mfma_f32_32x32x16_bf16 v[66:81], v[156:159], v[114:117], 0
	ds_read_b64_tr_b16 v[156:157], v193 offset:20736
	ds_read_b64_tr_b16 v[158:159], v193 offset:21888
	v_exp_f32_e32 v82, v82
	v_exp_f32_e32 v83, v83
	v_exp_f32_e32 v84, v84
	v_exp_f32_e32 v85, v85
	v_exp_f32_e32 v86, v86
	v_exp_f32_e32 v87, v87
	s_waitcnt lgkmcnt(6)
	v_mfma_f32_32x32x16_bf16 v[66:81], v[160:163], v[106:109], v[66:81]
	ds_read_b64_tr_b16 v[160:161], v193 offset:20800
	ds_read_b64_tr_b16 v[162:163], v193 offset:21952
	v_exp_f32_e32 v88, v88
	v_exp_f32_e32 v89, v89
	v_add_f32_e32 v150, v150, v82
	v_add_f32_e32 v150, v150, v83
	v_add_f32_e32 v150, v150, v84
	v_add_f32_e32 v150, v150, v85
	s_waitcnt lgkmcnt(6)
	v_mfma_f32_32x32x16_bf16 v[34:49], v[164:167], v[138:141], v[34:49]
	v_exp_f32_e32 v90, v90
	v_exp_f32_e32 v91, v91
	v_exp_f32_e32 v92, v92
	v_exp_f32_e32 v93, v93
	v_exp_f32_e32 v94, v94
	v_exp_f32_e32 v95, v95
	s_waitcnt lgkmcnt(4)
	v_mfma_f32_32x32x16_bf16 v[2:17], v[124:127], v[138:141], v[2:17]
	v_exp_f32_e32 v96, v96
	v_exp_f32_e32 v97, v97
	v_add_f32_e32 v150, v150, v86
	v_add_f32_e32 v150, v150, v87
	v_add_f32_e32 v150, v150, v88
	v_add_f32_e32 v150, v150, v89
	s_waitcnt lgkmcnt(2)
	v_mfma_f32_32x32x16_bf16 v[34:49], v[156:159], v[142:145], v[34:49]
	ds_read_b128 v[156:159], v192 offset:4672
	v_add_f32_e32 v150, v150, v90
	v_add_f32_e32 v150, v150, v91
	v_add_f32_e32 v150, v150, v92
	v_add_f32_e32 v150, v150, v93
	v_add_f32_e32 v150, v150, v94
	v_add_f32_e32 v150, v150, v95
	s_waitcnt lgkmcnt(1)
	v_mfma_f32_32x32x16_bf16 v[2:17], v[160:163], v[142:145], v[2:17]
	ds_read_b128 v[160:163], v192 offset:4704
	v_add_f32_e32 v150, v150, v96
	v_add_f32_e32 v150, v150, v97
	v_cvt_pk_bf16_f32 v146, v82, v83
	v_cvt_pk_bf16_f32 v147, v84, v85
	v_cvt_pk_bf16_f32 v148, v86, v87
	v_cvt_pk_bf16_f32 v149, v88, v89
	v_cvt_pk_bf16_f32 v152, v90, v91
	v_cvt_pk_bf16_f32 v153, v92, v93
	v_cvt_pk_bf16_f32 v154, v94, v95
	v_cvt_pk_bf16_f32 v155, v96, v97
	ds_read_b64_tr_b16 v[164:165], v193 offset:18432
	ds_read_b64_tr_b16 v[166:167], v193 offset:19584
	ds_read_b64_tr_b16 v[124:125], v193 offset:18496
	ds_read_b64_tr_b16 v[126:127], v193 offset:19648
	s_waitcnt lgkmcnt(5)
	v_mfma_f32_32x32x16_bf16 v[82:97], v[156:159], v[110:113], 0
	ds_read_b64_tr_b16 v[156:157], v193 offset:20736
	ds_read_b64_tr_b16 v[158:159], v193 offset:21888
	v_exp_f32_e32 v66, v66
	v_exp_f32_e32 v67, v67
	v_exp_f32_e32 v68, v68
	v_exp_f32_e32 v69, v69
	v_exp_f32_e32 v70, v70
	v_exp_f32_e32 v71, v71
	s_waitcnt lgkmcnt(6)
	v_mfma_f32_32x32x16_bf16 v[82:97], v[160:163], v[118:121], v[82:97]
	ds_read_b64_tr_b16 v[160:161], v193 offset:20800
	ds_read_b64_tr_b16 v[162:163], v193 offset:21952
	v_exp_f32_e32 v72, v72
	v_exp_f32_e32 v73, v73
	v_add_f32_e32 v151, v151, v66
	v_add_f32_e32 v151, v151, v67
	v_add_f32_e32 v151, v151, v68
	v_add_f32_e32 v151, v151, v69
	s_waitcnt lgkmcnt(6)
; #define LAS __attribute__((address_space(3)))
; #define MFMA32(a, b, c) __builtin_amdgcn_mfma_f32_32x32x16_bf16((a), (b), (c), 0, 0, 0)
; DI float fexp2(float x) { return __builtin_amdgcn_exp2f(x); }
; DI f32x16 zero16() { f32x16 z; for (int i = 0; i < 16; ++i) z[i] = 0.f; return z; }
; template <int MODE>
; DI void dense256_unit(const Params& p, int l, int b, int nq, int hd, LAS unsigned char* lds) {
;     ...
;       for (int mt = 0; mt < 2; ++mt) {
;         LAS unsigned char* krow = kt + (32 * mt + r) * W_RS + (8 * h) * 2;
;         const bf16x8 a0 = *(const LAS bf16x8*)(krow), a1 = *(const LAS bf16x8*)(krow + 32), a2 = *(const LAS bf16x8*)(krow + 64), a3 = *(const LAS bf16x8*)(krow + 96);
;         if (MODE == 0) {
;           f32x16 s1 = zero16(), s2 = zero16();
;           s1 = MFMA32(a0, qf[0], s1); s1 = MFMA32(a1, qf[1], s1); s2 = MFMA32(a2, qf[2], s2); s2 = MFMA32(a3, qf[3], s2);
; #pragma unroll
;           for (int i = 0; i < 16; ++i) { s1[i] = fexp2(s1[i]); l1 += s1[i]; s2[i] = fexp2(s2[i]); l2 += s2[i]; }
; #pragma unroll
;           for (int s = 0; s < 2; ++s) {
;             const bf16x8 p1 = pack8(s1, s), p2 = pack8(s2, s);
; #pragma unroll
;             for (int et = 0; et < 2; ++et) { const bf16x8 vf = vfrag144(vt, 32 * mt + 16 * s + 4 * h, 32 * et, lane); o1[et] = MFMA32(vf, p1, o1[et]); o2[et] = MFMA32(vf, p2, o2[et]); }
;           }
	v_mfma_f32_32x32x16_bf16 v[50:65], v[164:167], v[146:149], v[50:65]
	v_exp_f32_e32 v74, v74
	v_exp_f32_e32 v75, v75
	v_exp_f32_e32 v76, v76
	v_exp_f32_e32 v77, v77
	v_exp_f32_e32 v78, v78
	v_exp_f32_e32 v79, v79
	s_waitcnt lgkmcnt(4)
	v_mfma_f32_32x32x16_bf16 v[18:33], v[124:127], v[146:149], v[18:33]
	v_exp_f32_e32 v80, v80
	v_exp_f32_e32 v81, v81
	v_add_f32_e32 v151, v151, v70
	v_add_f32_e32 v151, v151, v71
	v_add_f32_e32 v151, v151, v72
	v_add_f32_e32 v151, v151, v73
	s_waitcnt lgkmcnt(2)
	v_mfma_f32_32x32x16_bf16 v[50:65], v[156:159], v[152:155], v[50:65]
	v_add_f32_e32 v151, v151, v74
	v_add_f32_e32 v151, v151, v75
	v_add_f32_e32 v151, v151, v76
	v_add_f32_e32 v151, v151, v77
	v_add_f32_e32 v151, v151, v78
	v_add_f32_e32 v151, v151, v79
	s_waitcnt lgkmcnt(0)
	v_mfma_f32_32x32x16_bf16 v[18:33], v[160:163], v[152:155], v[18:33]
	v_add_f32_e32 v151, v151, v80
	v_add_f32_e32 v151, v151, v81
	v_cvt_pk_bf16_f32 v138, v66, v67
	v_cvt_pk_bf16_f32 v139, v68, v69
	v_cvt_pk_bf16_f32 v140, v70, v71
	v_cvt_pk_bf16_f32 v141, v72, v73
	v_cvt_pk_bf16_f32 v142, v74, v75
	v_cvt_pk_bf16_f32 v143, v76, v77
	v_cvt_pk_bf16_f32 v144, v78, v79
	v_cvt_pk_bf16_f32 v145, v80, v81
	ds_read_b64_tr_b16 v[164:165], v193 offset:23040
	ds_read_b64_tr_b16 v[166:167], v193 offset:24192
	ds_read_b64_tr_b16 v[124:125], v193 offset:23104
	ds_read_b64_tr_b16 v[126:127], v193 offset:24256
	ds_read_b64_tr_b16 v[156:157], v193 offset:25344
	ds_read_b64_tr_b16 v[158:159], v193 offset:26496
	ds_read_b64_tr_b16 v[160:161], v193 offset:25408
	ds_read_b64_tr_b16 v[162:163], v193 offset:26560
	s_waitcnt lgkmcnt(6)
	v_mfma_f32_32x32x16_bf16 v[34:49], v[164:167], v[138:141], v[34:49]
	v_exp_f32_e32 v82, v82
	v_exp_f32_e32 v83, v83
	v_exp_f32_e32 v84, v84
	v_exp_f32_e32 v85, v85
	v_exp_f32_e32 v86, v86
	v_exp_f32_e32 v87, v87
	v_exp_f32_e32 v88, v88
	v_exp_f32_e32 v89, v89
	v_add_f32_e32 v150, v150, v82
	v_add_f32_e32 v150, v150, v83
	s_waitcnt lgkmcnt(4)
	v_mfma_f32_32x32x16_bf16 v[2:17], v[124:127], v[138:141], v[2:17]
	v_add_f32_e32 v150, v150, v84
	v_add_f32_e32 v150, v150, v85
	v_exp_f32_e32 v90, v90
	v_exp_f32_e32 v91, v91
	v_exp_f32_e32 v92, v92
	v_exp_f32_e32 v93, v93
	v_exp_f32_e32 v94, v94
	v_exp_f32_e32 v95, v95
	v_exp_f32_e32 v96, v96
	v_exp_f32_e32 v97, v97
	s_waitcnt lgkmcnt(2)
	v_mfma_f32_32x32x16_bf16 v[34:49], v[156:159], v[142:145], v[34:49]
	v_add_f32_e32 v150, v150, v86
	v_add_f32_e32 v150, v150, v87
	v_add_f32_e32 v150, v150, v88
	v_add_f32_e32 v150, v150, v89
	v_add_f32_e32 v150, v150, v90
	v_add_f32_e32 v150, v150, v91
	v_add_f32_e32 v150, v150, v92
	v_add_f32_e32 v150, v150, v93
	v_add_f32_e32 v150, v150, v94
	v_add_f32_e32 v150, v150, v95
	s_waitcnt lgkmcnt(0)
	v_mfma_f32_32x32x16_bf16 v[2:17], v[160:163], v[142:145], v[2:17]
	v_add_f32_e32 v150, v150, v96
	v_add_f32_e32 v150, v150, v97
	v_cvt_pk_bf16_f32 v146, v82, v83
	v_cvt_pk_bf16_f32 v147, v84, v85
	v_cvt_pk_bf16_f32 v148, v86, v87
	v_cvt_pk_bf16_f32 v149, v88, v89
	v_cvt_pk_bf16_f32 v152, v90, v91
	v_cvt_pk_bf16_f32 v153, v92, v93
	v_cvt_pk_bf16_f32 v154, v94, v95
	v_cvt_pk_bf16_f32 v155, v96, v97
	ds_read_b64_tr_b16 v[164:165], v193 offset:23040
	ds_read_b64_tr_b16 v[166:167], v193 offset:24192
	ds_read_b64_tr_b16 v[124:125], v193 offset:23104
	ds_read_b64_tr_b16 v[126:127], v193 offset:24256
	ds_read_b64_tr_b16 v[156:157], v193 offset:25344
	ds_read_b64_tr_b16 v[158:159], v193 offset:26496
	ds_read_b64_tr_b16 v[160:161], v193 offset:25408
	ds_read_b64_tr_b16 v[162:163], v193 offset:26560
	s_waitcnt lgkmcnt(6)
	v_mfma_f32_32x32x16_bf16 v[50:65], v[164:167], v[146:149], v[50:65]
	s_waitcnt lgkmcnt(4)
	v_mfma_f32_32x32x16_bf16 v[18:33], v[124:127], v[146:149], v[18:33]
	s_waitcnt lgkmcnt(2)
	v_mfma_f32_32x32x16_bf16 v[50:65], v[156:159], v[152:155], v[50:65]
	s_waitcnt lgkmcnt(0)
	v_mfma_f32_32x32x16_bf16 v[18:33], v[160:163], v[152:155], v[18:33]
	s_branch .Lmy_diff_done
.Lmy_diff_buf1:
	ds_read_b128 v[156:159], v192 offset:9216
	ds_read_b128 v[160:163], v192 offset:9248
	s_waitcnt lgkmcnt(1)
	v_mfma_f32_32x32x16_bf16 v[66:81], v[156:159], v[114:117], 0
	ds_read_b128 v[156:159], v192 offset:9280
	s_waitcnt lgkmcnt(1)
	v_mfma_f32_32x32x16_bf16 v[66:81], v[160:163], v[106:109], v[66:81]
	ds_read_b128 v[160:163], v192 offset:9312
	s_nop 10
	s_waitcnt lgkmcnt(1)
	v_mfma_f32_32x32x16_bf16 v[82:97], v[156:159], v[110:113], 0
	ds_read_b128 v[156:159], v192 offset:13824
	v_exp_f32_e32 v66, v66
	v_exp_f32_e32 v67, v67
	v_exp_f32_e32 v68, v68
	v_exp_f32_e32 v69, v69
	v_exp_f32_e32 v70, v70
	v_exp_f32_e32 v71, v71
	v_exp_f32_e32 v72, v72
	v_exp_f32_e32 v73, v73
	v_add_f32_e32 v151, v151, v66
	v_add_f32_e32 v151, v151, v67
	v_add_f32_e32 v151, v151, v68
	v_add_f32_e32 v151, v151, v69
	v_exp_f32_e32 v74, v74
	v_exp_f32_e32 v75, v75
	v_exp_f32_e32 v76, v76
	v_exp_f32_e32 v77, v77
	v_exp_f32_e32 v78, v78
	v_exp_f32_e32 v79, v79
	v_exp_f32_e32 v80, v80
	v_exp_f32_e32 v81, v81
	s_waitcnt lgkmcnt(1)
	v_mfma_f32_32x32x16_bf16 v[82:97], v[160:163], v[118:121], v[82:97]
	ds_read_b128 v[160:163], v192 offset:13856
	v_add_f32_e32 v151, v151, v70
	v_add_f32_e32 v151, v151, v71
	v_add_f32_e32 v151, v151, v72
	v_add_f32_e32 v151, v151, v73
	v_add_f32_e32 v151, v151, v74
	v_add_f32_e32 v151, v151, v75
	v_add_f32_e32 v151, v151, v76
	v_add_f32_e32 v151, v151, v77
	v_add_f32_e32 v151, v151, v78
	v_add_f32_e32 v151, v151, v79
	v_add_f32_e32 v151, v151, v80
	v_add_f32_e32 v151, v151, v81
	v_cvt_pk_bf16_f32 v138, v66, v67
	v_cvt_pk_bf16_f32 v139, v68, v69
	v_cvt_pk_bf16_f32 v140, v70, v71
	v_cvt_pk_bf16_f32 v141, v72, v73
	v_cvt_pk_bf16_f32 v142, v74, v75
	v_cvt_pk_bf16_f32 v143, v76, v77
	v_cvt_pk_bf16_f32 v144, v78, v79
	v_cvt_pk_bf16_f32 v145, v80, v81
	ds_read_b64_tr_b16 v[164:165], v193 offset:27648
	ds_read_b64_tr_b16 v[166:167], v193 offset:28800
	ds_read_b64_tr_b16 v[124:125], v193 offset:27712
	ds_read_b64_tr_b16 v[126:127], v193 offset:28864
	s_waitcnt lgkmcnt(5)
; #define LAS __attribute__((address_space(3)))
; #define MFMA32(a, b, c) __builtin_amdgcn_mfma_f32_32x32x16_bf16((a), (b), (c), 0, 0, 0)
; DI float fexp2(float x) { return __builtin_amdgcn_exp2f(x); }
; DI f32x16 zero16() { f32x16 z; for (int i = 0; i < 16; ++i) z[i] = 0.f; return z; }
; template <int MODE>
; DI void dense256_unit(const Params& p, int l, int b, int nq, int hd, LAS unsigned char* lds) {
;     ...
;       for (int mt = 0; mt < 2; ++mt) {
;         LAS unsigned char* krow = kt + (32 * mt + r) * W_RS + (8 * h) * 2;
;         const bf16x8 a0 = *(const LAS bf16x8*)(krow), a1 = *(const LAS bf16x8*)(krow + 32), a2 = *(const LAS bf16x8*)(krow + 64), a3 = *(const LAS bf16x8*)(krow + 96);
;         if (MODE == 0) {
;           f32x16 s1 = zero16(), s2 = zero16();
;           s1 = MFMA32(a0, qf[0], s1); s1 = MFMA32(a1, qf[1], s1); s2 = MFMA32(a2, qf[2], s2); s2 = MFMA32(a3, qf[3], s2);
; #pragma unroll
;           for (int i = 0; i < 16; ++i) { s1[i] = fexp2(s1[i]); l1 += s1[i]; s2[i] = fexp2(s2[i]); l2 += s2[i]; }
; #pragma unroll
;           for (int s = 0; s < 2; ++s) {
;             const bf16x8 p1 = pack8(s1, s), p2 = pack8(s2, s);
; #pragma unroll
;             for (int et = 0; et < 2; ++et) { const bf16x8 vf = vfrag144(vt, 32 * mt + 16 * s + 4 * h, 32 * et, lane); o1[et] = MFMA32(vf, p1, o1[et]); o2[et] = MFMA32(vf, p2, o2[et]); }
;           }
	v_mfma_f32_32x32x16_bf16 v[66:81], v[156:159], v[114:117], 0
	ds_read_b64_tr_b16 v[156:157], v193 offset:29952
	ds_read_b64_tr_b16 v[158:159], v193 offset:31104
	v_exp_f32_e32 v82, v82
	v_exp_f32_e32 v83, v83
	v_exp_f32_e32 v84, v84
	v_exp_f32_e32 v85, v85
	v_exp_f32_e32 v86, v86
	v_exp_f32_e32 v87, v87
	s_waitcnt lgkmcnt(6)
	v_mfma_f32_32x32x16_bf16 v[66:81], v[160:163], v[106:109], v[66:81]
	ds_read_b64_tr_b16 v[160:161], v193 offset:30016
	ds_read_b64_tr_b16 v[162:163], v193 offset:31168
	v_exp_f32_e32 v88, v88
	v_exp_f32_e32 v89, v89
	v_add_f32_e32 v150, v150, v82
	v_add_f32_e32 v150, v150, v83
	v_add_f32_e32 v150, v150, v84
	v_add_f32_e32 v150, v150, v85
	s_waitcnt lgkmcnt(6)
	v_mfma_f32_32x32x16_bf16 v[34:49], v[164:167], v[138:141], v[34:49]
	v_exp_f32_e32 v90, v90
	v_exp_f32_e32 v91, v91
	v_exp_f32_e32 v92, v92
	v_exp_f32_e32 v93, v93
	v_exp_f32_e32 v94, v94
	v_exp_f32_e32 v95, v95
	s_waitcnt lgkmcnt(4)
	v_mfma_f32_32x32x16_bf16 v[2:17], v[124:127], v[138:141], v[2:17]
	v_exp_f32_e32 v96, v96
	v_exp_f32_e32 v97, v97
	v_add_f32_e32 v150, v150, v86
	v_add_f32_e32 v150, v150, v87
	v_add_f32_e32 v150, v150, v88
	v_add_f32_e32 v150, v150, v89
	s_waitcnt lgkmcnt(2)
	v_mfma_f32_32x32x16_bf16 v[34:49], v[156:159], v[142:145], v[34:49]
	ds_read_b128 v[156:159], v192 offset:13888
	v_add_f32_e32 v150, v150, v90
	v_add_f32_e32 v150, v150, v91
	v_add_f32_e32 v150, v150, v92
	v_add_f32_e32 v150, v150, v93
	v_add_f32_e32 v150, v150, v94
	v_add_f32_e32 v150, v150, v95
	s_waitcnt lgkmcnt(1)
	v_mfma_f32_32x32x16_bf16 v[2:17], v[160:163], v[142:145], v[2:17]
	ds_read_b128 v[160:163], v192 offset:13920
	v_add_f32_e32 v150, v150, v96
	v_add_f32_e32 v150, v150, v97
	v_cvt_pk_bf16_f32 v146, v82, v83
	v_cvt_pk_bf16_f32 v147, v84, v85
	v_cvt_pk_bf16_f32 v148, v86, v87
	v_cvt_pk_bf16_f32 v149, v88, v89
	v_cvt_pk_bf16_f32 v152, v90, v91
	v_cvt_pk_bf16_f32 v153, v92, v93
	v_cvt_pk_bf16_f32 v154, v94, v95
	v_cvt_pk_bf16_f32 v155, v96, v97
	ds_read_b64_tr_b16 v[164:165], v193 offset:27648
	ds_read_b64_tr_b16 v[166:167], v193 offset:28800
	ds_read_b64_tr_b16 v[124:125], v193 offset:27712
	ds_read_b64_tr_b16 v[126:127], v193 offset:28864
	s_waitcnt lgkmcnt(5)
	v_mfma_f32_32x32x16_bf16 v[82:97], v[156:159], v[110:113], 0
	ds_read_b64_tr_b16 v[156:157], v193 offset:29952
	ds_read_b64_tr_b16 v[158:159], v193 offset:31104
	v_exp_f32_e32 v66, v66
	v_exp_f32_e32 v67, v67
	v_exp_f32_e32 v68, v68
	v_exp_f32_e32 v69, v69
	v_exp_f32_e32 v70, v70
	v_exp_f32_e32 v71, v71
	s_waitcnt lgkmcnt(6)
	v_mfma_f32_32x32x16_bf16 v[82:97], v[160:163], v[118:121], v[82:97]
	ds_read_b64_tr_b16 v[160:161], v193 offset:30016
	ds_read_b64_tr_b16 v[162:163], v193 offset:31168
	v_exp_f32_e32 v72, v72
	v_exp_f32_e32 v73, v73
	v_add_f32_e32 v151, v151, v66
	v_add_f32_e32 v151, v151, v67
	v_add_f32_e32 v151, v151, v68
	v_add_f32_e32 v151, v151, v69
	s_waitcnt lgkmcnt(6)
	v_mfma_f32_32x32x16_bf16 v[50:65], v[164:167], v[146:149], v[50:65]
	v_exp_f32_e32 v74, v74
	v_exp_f32_e32 v75, v75
	v_exp_f32_e32 v76, v76
	v_exp_f32_e32 v77, v77
	v_exp_f32_e32 v78, v78
	v_exp_f32_e32 v79, v79
	s_waitcnt lgkmcnt(4)
	v_mfma_f32_32x32x16_bf16 v[18:33], v[124:127], v[146:149], v[18:33]
	v_exp_f32_e32 v80, v80
	v_exp_f32_e32 v81, v81
	v_add_f32_e32 v151, v151, v70
	v_add_f32_e32 v151, v151, v71
	v_add_f32_e32 v151, v151, v72
	v_add_f32_e32 v151, v151, v73
	s_waitcnt lgkmcnt(2)
	v_mfma_f32_32x32x16_bf16 v[50:65], v[156:159], v[152:155], v[50:65]
	v_add_f32_e32 v151, v151, v74
	v_add_f32_e32 v151, v151, v75
	v_add_f32_e32 v151, v151, v76
	v_add_f32_e32 v151, v151, v77
	v_add_f32_e32 v151, v151, v78
	v_add_f32_e32 v151, v151, v79
	s_waitcnt lgkmcnt(0)
	v_mfma_f32_32x32x16_bf16 v[18:33], v[160:163], v[152:155], v[18:33]
	v_add_f32_e32 v151, v151, v80
	v_add_f32_e32 v151, v151, v81
	v_cvt_pk_bf16_f32 v138, v66, v67
	v_cvt_pk_bf16_f32 v139, v68, v69
	v_cvt_pk_bf16_f32 v140, v70, v71
	v_cvt_pk_bf16_f32 v141, v72, v73
	v_cvt_pk_bf16_f32 v142, v74, v75
	v_cvt_pk_bf16_f32 v143, v76, v77
	v_cvt_pk_bf16_f32 v144, v78, v79
	v_cvt_pk_bf16_f32 v145, v80, v81
	ds_read_b64_tr_b16 v[164:165], v193 offset:32256
	ds_read_b64_tr_b16 v[166:167], v193 offset:33408
	ds_read_b64_tr_b16 v[124:125], v193 offset:32320
	ds_read_b64_tr_b16 v[126:127], v193 offset:33472
	ds_read_b64_tr_b16 v[156:157], v193 offset:34560
	ds_read_b64_tr_b16 v[158:159], v193 offset:35712
	ds_read_b64_tr_b16 v[160:161], v193 offset:34624
	ds_read_b64_tr_b16 v[162:163], v193 offset:35776
	s_waitcnt lgkmcnt(6)
	v_mfma_f32_32x32x16_bf16 v[34:49], v[164:167], v[138:141], v[34:49]
	v_exp_f32_e32 v82, v82
	v_exp_f32_e32 v83, v83
	v_exp_f32_e32 v84, v84
	v_exp_f32_e32 v85, v85
	v_exp_f32_e32 v86, v86
	v_exp_f32_e32 v87, v87
	v_exp_f32_e32 v88, v88
	v_exp_f32_e32 v89, v89
	v_add_f32_e32 v150, v150, v82
	v_add_f32_e32 v150, v150, v83
	s_waitcnt lgkmcnt(4)
	v_mfma_f32_32x32x16_bf16 v[2:17], v[124:127], v[138:141], v[2:17]
	v_add_f32_e32 v150, v150, v84
	v_add_f32_e32 v150, v150, v85
	v_exp_f32_e32 v90, v90
	v_exp_f32_e32 v91, v91
	v_exp_f32_e32 v92, v92
	v_exp_f32_e32 v93, v93
	v_exp_f32_e32 v94, v94
	v_exp_f32_e32 v95, v95
	v_exp_f32_e32 v96, v96
	v_exp_f32_e32 v97, v97
	s_waitcnt lgkmcnt(2)
	v_mfma_f32_32x32x16_bf16 v[34:49], v[156:159], v[142:145], v[34:49]
	v_add_f32_e32 v150, v150, v86
	v_add_f32_e32 v150, v150, v87
	v_add_f32_e32 v150, v150, v88
	v_add_f32_e32 v150, v150, v89
	v_add_f32_e32 v150, v150, v90
	v_add_f32_e32 v150, v150, v91
	v_add_f32_e32 v150, v150, v92
	v_add_f32_e32 v150, v150, v93
	v_add_f32_e32 v150, v150, v94
	v_add_f32_e32 v150, v150, v95
	s_waitcnt lgkmcnt(0)
	v_mfma_f32_32x32x16_bf16 v[2:17], v[160:163], v[142:145], v[2:17]
	v_add_f32_e32 v150, v150, v96
	v_add_f32_e32 v150, v150, v97
	v_cvt_pk_bf16_f32 v146, v82, v83
	v_cvt_pk_bf16_f32 v147, v84, v85
	v_cvt_pk_bf16_f32 v148, v86, v87
	v_cvt_pk_bf16_f32 v149, v88, v89
	v_cvt_pk_bf16_f32 v152, v90, v91
	v_cvt_pk_bf16_f32 v153, v92, v93
	v_cvt_pk_bf16_f32 v154, v94, v95
	v_cvt_pk_bf16_f32 v155, v96, v97
	ds_read_b64_tr_b16 v[164:165], v193 offset:32256
	ds_read_b64_tr_b16 v[166:167], v193 offset:33408
	ds_read_b64_tr_b16 v[124:125], v193 offset:32320
	ds_read_b64_tr_b16 v[126:127], v193 offset:33472
	ds_read_b64_tr_b16 v[156:157], v193 offset:34560
	ds_read_b64_tr_b16 v[158:159], v193 offset:35712
	ds_read_b64_tr_b16 v[160:161], v193 offset:34624
	ds_read_b64_tr_b16 v[162:163], v193 offset:35776
	s_waitcnt lgkmcnt(6)
	v_mfma_f32_32x32x16_bf16 v[50:65], v[164:167], v[146:149], v[50:65]
	s_waitcnt lgkmcnt(4)
	v_mfma_f32_32x32x16_bf16 v[18:33], v[124:127], v[146:149], v[18:33]
	s_waitcnt lgkmcnt(2)
	v_mfma_f32_32x32x16_bf16 v[50:65], v[156:159], v[152:155], v[50:65]
	s_waitcnt lgkmcnt(0)
	v_mfma_f32_32x32x16_bf16 v[18:33], v[160:163], v[152:155], v[18:33]
; template <int MODE>
; DI void dense256_unit(const Params& p, int l, int b, int nq, int hd, LAS unsigned char* lds) {
;     ...
;   float y[2][16];
;   if (MODE == 0) {
;     l1 += __shfl_xor(l1, 32); l2 += __shfl_xor(l2, 32);
.Lmy_diff_done:
	s_or_b64 exec, exec, s[8:9]
	s_andn2_b64 vcc, exec, s[6:7]
	s_cbranch_vccz .LBB0_969
	s_branch .LBB0_970
.LBB0_974:
	v_mov_b64_e32 v[130:131], 0x1100
	v_mov_b64_e32 v[132:133], 0x10ff
	v_mov_b64_e32 v[134:135], 0x400
	v_mov_b64_e32 v[136:137], 0x3ff
	v_lshlrev_b32_e32 v66, 4, v168
	ds_read_b128 v[124:127], v66 offset:40960
	s_waitcnt lgkmcnt(0)
	v_and_b32_e32 v66, 64, v181
	v_xor_b32_e32 v0, 32, v181
	v_add_u32_e32 v66, 64, v66
	v_cmp_lt_i32_e32 vcc, v0, v66
	v_mov_b32_e32 v68, 0
	v_mov_b32_e32 v69, 0
	v_cndmask_b32_e32 v0, v181, v0, vcc
	v_lshlrev_b32_e32 v81, 2, v0
	ds_bpermute_b32 v70, v81, v151
	ds_bpermute_b32 v67, v81, v150
	v_cmp_gt_u32_e32 vcc, 32, v190
	s_and_saveexec_b64 s[6:7], vcc
	s_cbranch_execz .LBB0_976
	v_readlane_b32 s2, v251, 58
	v_readlane_b32 s12, v252, 25
	v_readlane_b32 s18, v252, 31
	v_or_b32_e32 v0, s2, v190
	v_lshlrev_b64 v[68:69], 2, v[0:1]
	v_readlane_b32 s19, v252, 32
	v_readlane_b32 s20, v252, 33
	v_readlane_b32 s21, v252, 34
	v_readlane_b32 s22, v252, 35
	v_readlane_b32 s23, v252, 36
	v_readlane_b32 s24, v252, 37
	v_readlane_b32 s25, v252, 38
	v_lshl_add_u64 v[72:73], s[18:19], 0, v[68:69]
	v_lshl_add_u64 v[74:75], s[20:21], 0, v[68:69]
	v_lshl_add_u64 v[76:77], s[22:23], 0, v[68:69]
	v_lshl_add_u64 v[68:69], s[24:25], 0, v[68:69]
	global_load_dword v72, v[72:73], off
	v_readlane_b32 s13, v252, 26
	global_load_dword v74, v[74:75], off
	v_readlane_b32 s14, v252, 27
	global_load_dword v73, v[76:77], off
	global_load_dword v75, v[68:69], off
	v_readlane_b32 s15, v252, 28
	v_readlane_b32 s16, v252, 29
	v_readlane_b32 s17, v252, 30
	v_readlane_b32 s26, v252, 39
	v_readlane_b32 s27, v252, 40
	s_waitcnt vmcnt(0)
	v_pk_fma_f32 v[68:69], v[72:73], v[74:75], 0 op_sel_hi:[1,1,0]
